# grid barrier: the 3/4-th arriving workgroup of each XCD issues one early buffer_wbl2 so the leader's write-back has less to flush
# baseline (speedup 1.0000x reference)
; __device__ __forceinline__ unsigned xb_ld(unsigned* p)              { return __hip_atomic_load(p, __ATOMIC_RELAXED, __HIP_MEMORY_SCOPE_AGENT); }
; __device__ __forceinline__ unsigned xb_add(unsigned* p, unsigned v) { return __hip_atomic_fetch_add(p, v, __ATOMIC_RELAXED, __HIP_MEMORY_SCOPE_AGENT); }
; #define XB_SPIN(cond, bar) do { unsigned _sp = 0; while (cond) { __builtin_amdgcn_s_sleep(1); \
;     if ((++_sp & 255u) == 0u) { if (xb_ld(&(bar)[XB_TMO])) break; if (_sp > XB_SPIN_CAP) { atomicAdd(&(bar)[XB_TMO], 1u); break; } } } } while (0)
; __device__ __forceinline__ void xcd_barrier(const XcdBarrier& b, const bool xb_is_leader) {
;     ...
;         const unsigned old = xb_add(&bar[XB_XSUB(b.x)], 1u);
;         const unsigned gen = old / nloc;
;         if (old + 1u == (gen + 1u) * nloc) {
;             __builtin_amdgcn_fence(__ATOMIC_RELEASE, "agent");
;             asm volatile("s_waitcnt vmcnt(0)" ::: "memory");
;             const unsigned og = xb_add(&bar[XB_TOP], 1u);
;             const unsigned tg = og / nx;
;             if (og + 1u == (tg + 1u) * nx) xb_add(&bar[XB_TOPGEN], 1u);
;             else XB_SPIN(xb_ld(&bar[XB_TOPGEN]) == tg, bar);
;             __builtin_amdgcn_fence(__ATOMIC_ACQUIRE, "agent");
;             xb_add(&bar[XB_XGEN(b.x)], 1u);
;             asm volatile("s_waitcnt vmcnt(0)" ::: "memory");
;         } else {
;             XB_SPIN(xb_ld(&bar[XB_XGEN(b.x)]) == gen, bar);
.LBB0_204:
	s_or_b64 exec, exec, s[8:9]
	v_cvt_f32_u32_e32 v4, v2
	s_waitcnt vmcnt(0)
	v_readfirstlane_b32 s0, v3
	v_sub_u32_e32 v3, 0, v2
	v_rcp_iflag_f32_e32 v4, v4
	v_add_u32_e32 v5, s0, v1
	v_mul_f32_e32 v4, 0x4f7ffffe, v4
	v_cvt_u32_f32_e32 v4, v4
	v_mul_lo_u32 v1, v3, v4
	v_mul_hi_u32 v1, v4, v1
	v_add_u32_e32 v1, v4, v1
	v_mul_hi_u32 v1, v5, v1
	v_mul_lo_u32 v3, v1, v2
	v_sub_u32_e32 v3, v5, v3
	v_add_u32_e32 v4, 1, v1
	v_cmp_ge_u32_e32 vcc, v3, v2
	s_nop 1
	v_cndmask_b32_e32 v1, v1, v4, vcc
	v_sub_u32_e32 v4, v3, v2
	v_cndmask_b32_e32 v3, v3, v4, vcc
	v_add_u32_e32 v4, 1, v1
	v_cmp_ge_u32_e32 vcc, v3, v2
	v_add_u32_e32 v3, 1, v5
	s_nop 0
	v_cndmask_b32_e32 v1, v1, v4, vcc
	v_mul_lo_u32 v4, v2, v1
	v_add_u32_e32 v2, v4, v2
	v_cmp_ne_u32_e32 vcc, v3, v2
	s_and_saveexec_b64 s[0:1], vcc
	s_xor_b64 s[0:1], exec, s[0:1]
	s_cbranch_execz .LBB0_218
	s_waitcnt lgkmcnt(0)
	v_sub_u32_e32 v0, v2, v4
	v_lshrrev_b32_e32 v0, 2, v0
	v_sub_u32_e32 v0, v2, v0
	v_cmp_eq_u32_e32 vcc, v5, v0
	s_cbranch_vccz .Lxb_noflush_1
	buffer_wbl2 sc1
.Lxb_noflush_1:
	v_mov_b32_e32 v0, 0x2000
	global_load_dword v0, v0, s[6:7] offset:1024 sc1
	s_add_u32 s10, s6, 0x2400
	s_addc_u32 s11, s7, 0
	s_waitcnt vmcnt(0)
	v_cmp_eq_u32_e32 vcc, v0, v1
	s_and_saveexec_b64 s[8:9], vcc
	s_cbranch_execz .LBB0_217
	s_mov_b32 s2, 1
	s_mov_b64 s[12:13], 0
	v_mov_b32_e32 v0, 0
	s_branch .LBB0_208
